# MoBA: softmax exp/sum/convert of key chunk c+1 interleaved with PV MFMAs of chunk c (software pipelined within the wave)
# speedup vs baseline: 1.0052x; 1.0052x over previous
.LBB0_156:
	ds_read_b128 v[238:241], v195 offset:52224
	ds_read_b128 v[242:245], v195 offset:52496
	ds_read_b128 v[246:249], v195 offset:60928
	ds_read_b128 v[198:201], v195 offset:61200
	v_mov_b32_e32 v250, v197
	s_nop 1
	v_permlane16_swap_b32_e32 v197, v250
	v_max_f32_e32 v197, v197, v250
	v_mov_b32_e32 v250, v197
	s_nop 1
	v_permlane32_swap_b32_e32 v197, v250
	v_max3_f32 v197, v196, v197, v250
	v_cmp_neq_f32_e32 vcc, s73, v197
	s_nop 1
	v_cndmask_b32_e32 v250, 0, v197, vcc
	v_sub_f32_e32 v196, v196, v250
	v_mul_f32_e32 v251, 0x3e0293ee, v196
	v_mul_f32_e32 v196, 0xbe0293ee, v250
	v_cndmask_b32_e64 v250, v196, v215, s[0:1]
	v_exp_f32_e32 v224, v251
	v_fmamk_f32 v112, v112, 0x3e0293ee, v250
	v_exp_f32_e32 v112, v112
	v_fmamk_f32 v113, v113, 0x3e0293ee, v250
	v_exp_f32_e32 v113, v113
	v_fmamk_f32 v114, v114, 0x3e0293ee, v250
	v_exp_f32_e32 v114, v114
	v_fmamk_f32 v115, v115, 0x3e0293ee, v250
	v_exp_f32_e32 v115, v115
	v_fmamk_f32 v108, v108, 0x3e0293ee, v250
	v_add_f32_e32 v196, 0, v112
	v_exp_f32_e32 v108, v108
	v_fmamk_f32 v109, v109, 0x3e0293ee, v250
	v_add_f32_e32 v196, v113, v196
	v_exp_f32_e32 v109, v109
	v_fmamk_f32 v110, v110, 0x3e0293ee, v250
	v_add_f32_e32 v196, v114, v196
	v_exp_f32_e32 v110, v110
	v_fmamk_f32 v111, v111, 0x3e0293ee, v250
	v_add_f32_e32 v196, v115, v196
	v_exp_f32_e32 v111, v111
	v_cmp_neq_f32_e32 vcc, 1.0, v224
	s_nop 0
	s_cbranch_vccz .Lmp_nr
	v_pk_mul_f32 v[82:83], v[82:83], v[224:225] op_sel_hi:[1,0]
	v_pk_mul_f32 v[80:81], v[80:81], v[224:225] op_sel_hi:[1,0]
	v_pk_mul_f32 v[78:79], v[78:79], v[224:225] op_sel_hi:[1,0]
	v_pk_mul_f32 v[76:77], v[76:77], v[224:225] op_sel_hi:[1,0]
	v_pk_mul_f32 v[74:75], v[74:75], v[224:225] op_sel_hi:[1,0]
	v_pk_mul_f32 v[72:73], v[72:73], v[224:225] op_sel_hi:[1,0]
	v_pk_mul_f32 v[70:71], v[70:71], v[224:225] op_sel_hi:[1,0]
	v_pk_mul_f32 v[68:69], v[68:69], v[224:225] op_sel_hi:[1,0]
	v_pk_mul_f32 v[66:67], v[66:67], v[224:225] op_sel_hi:[1,0]
	v_pk_mul_f32 v[64:65], v[64:65], v[224:225] op_sel_hi:[1,0]
	v_pk_mul_f32 v[62:63], v[62:63], v[224:225] op_sel_hi:[1,0]
	v_pk_mul_f32 v[60:61], v[60:61], v[224:225] op_sel_hi:[1,0]
	v_pk_mul_f32 v[58:59], v[58:59], v[224:225] op_sel_hi:[1,0]
	v_pk_mul_f32 v[56:57], v[56:57], v[224:225] op_sel_hi:[1,0]
	v_pk_mul_f32 v[54:55], v[54:55], v[224:225] op_sel_hi:[1,0]
	v_pk_mul_f32 v[52:53], v[52:53], v[224:225] op_sel_hi:[1,0]
.Lmp_nr:
	v_cvt_pk_bf16_f32 v112, v112, v113
	v_cvt_pk_bf16_f32 v113, v114, v115
	v_cvt_pk_bf16_f32 v114, v108, v109
	v_cvt_pk_bf16_f32 v115, v110, v111
	s_nop 1
	s_waitcnt lgkmcnt(4)
	v_mfma_f32_16x16x32_bf16 v[80:83], v[202:205], v[112:115], v[80:83]
	v_fmamk_f32 v104, v104, 0x3e0293ee, v250
	v_add_f32_e32 v196, v108, v196
	v_exp_f32_e32 v104, v104
	v_mfma_f32_16x16x32_bf16 v[76:79], v[206:209], v[112:115], v[76:79]
	v_fmamk_f32 v105, v105, 0x3e0293ee, v250
	v_add_f32_e32 v196, v109, v196
	v_exp_f32_e32 v105, v105
	v_mfma_f32_16x16x32_bf16 v[72:75], v[230:233], v[112:115], v[72:75]
	v_fmamk_f32 v106, v106, 0x3e0293ee, v250
	v_add_f32_e32 v196, v110, v196
	v_exp_f32_e32 v106, v106
	v_mfma_f32_16x16x32_bf16 v[68:71], v[234:237], v[112:115], v[68:71]
	v_fmamk_f32 v107, v107, 0x3e0293ee, v250
	v_add_f32_e32 v196, v111, v196
	v_exp_f32_e32 v107, v107
	ds_read_b128 v[202:205], v195 offset:34880
	ds_read_b128 v[206:209], v195 offset:35152
	ds_read_b128 v[230:233], v195 offset:43584
	ds_read_b128 v[234:237], v195 offset:43856
	s_waitcnt lgkmcnt(4)
	v_mfma_f32_16x16x32_bf16 v[64:67], v[238:241], v[112:115], v[64:67]
	v_fmamk_f32 v100, v100, 0x3e0293ee, v250
	v_add_f32_e32 v196, v104, v196
	v_exp_f32_e32 v100, v100
	v_mfma_f32_16x16x32_bf16 v[60:63], v[242:245], v[112:115], v[60:63]
	v_fmamk_f32 v101, v101, 0x3e0293ee, v250
	v_add_f32_e32 v196, v105, v196
	v_exp_f32_e32 v101, v101
	v_mfma_f32_16x16x32_bf16 v[56:59], v[246:249], v[112:115], v[56:59]
	v_fmamk_f32 v102, v102, 0x3e0293ee, v250
	v_add_f32_e32 v196, v106, v196
	v_exp_f32_e32 v102, v102
	v_mfma_f32_16x16x32_bf16 v[52:55], v[198:201], v[112:115], v[52:55]
	v_fmamk_f32 v103, v103, 0x3e0293ee, v250
	v_add_f32_e32 v196, v107, v196
	v_exp_f32_e32 v103, v103
	v_cvt_pk_bf16_f32 v104, v104, v105
	v_cvt_pk_bf16_f32 v105, v106, v107
	v_cvt_pk_bf16_f32 v106, v100, v101
	v_cvt_pk_bf16_f32 v107, v102, v103
	ds_read_b128 v[238:241], v195 offset:52288
	ds_read_b128 v[242:245], v195 offset:52560
	ds_read_b128 v[246:249], v195 offset:60992
	ds_read_b128 v[198:201], v195 offset:61264
	s_waitcnt lgkmcnt(4)
	v_mfma_f32_16x16x32_bf16 v[80:83], v[202:205], v[104:107], v[80:83]
	v_fmamk_f32 v96, v96, 0x3e0293ee, v250
	v_add_f32_e32 v196, v100, v196
	v_exp_f32_e32 v96, v96
	v_mfma_f32_16x16x32_bf16 v[76:79], v[206:209], v[104:107], v[76:79]
	v_fmamk_f32 v97, v97, 0x3e0293ee, v250
	v_add_f32_e32 v196, v101, v196
	v_exp_f32_e32 v97, v97
	v_mfma_f32_16x16x32_bf16 v[72:75], v[230:233], v[104:107], v[72:75]
	v_fmamk_f32 v98, v98, 0x3e0293ee, v250
	v_add_f32_e32 v196, v102, v196
	v_exp_f32_e32 v98, v98
	v_mfma_f32_16x16x32_bf16 v[68:71], v[234:237], v[104:107], v[68:71]
	v_fmamk_f32 v99, v99, 0x3e0293ee, v250
	v_add_f32_e32 v196, v103, v196
	v_exp_f32_e32 v99, v99
	ds_read_b128 v[202:205], v195 offset:34944
	ds_read_b128 v[206:209], v195 offset:35216
	ds_read_b128 v[230:233], v195 offset:43648
	ds_read_b128 v[234:237], v195 offset:43920
	s_waitcnt lgkmcnt(4)
	v_mfma_f32_16x16x32_bf16 v[64:67], v[238:241], v[104:107], v[64:67]
	v_fmamk_f32 v92, v92, 0x3e0293ee, v250
	v_add_f32_e32 v196, v96, v196
	v_exp_f32_e32 v92, v92
	v_mfma_f32_16x16x32_bf16 v[60:63], v[242:245], v[104:107], v[60:63]
	v_fmamk_f32 v93, v93, 0x3e0293ee, v250
	v_add_f32_e32 v196, v97, v196
	v_exp_f32_e32 v93, v93
	v_mfma_f32_16x16x32_bf16 v[56:59], v[246:249], v[104:107], v[56:59]
	v_fmamk_f32 v94, v94, 0x3e0293ee, v250
	v_add_f32_e32 v196, v98, v196
	v_exp_f32_e32 v94, v94
	v_mfma_f32_16x16x32_bf16 v[52:55], v[198:201], v[104:107], v[52:55]
	v_fmamk_f32 v95, v95, 0x3e0293ee, v250
	v_add_f32_e32 v196, v99, v196
	v_exp_f32_e32 v95, v95
	v_cvt_pk_bf16_f32 v96, v96, v97
	v_cvt_pk_bf16_f32 v97, v98, v99
	v_cvt_pk_bf16_f32 v98, v92, v93
	v_cvt_pk_bf16_f32 v99, v94, v95
	ds_read_b128 v[238:241], v195 offset:52352
	ds_read_b128 v[242:245], v195 offset:52624
	ds_read_b128 v[246:249], v195 offset:61056
	ds_read_b128 v[198:201], v195 offset:61328
	s_waitcnt lgkmcnt(4)
	v_mfma_f32_16x16x32_bf16 v[80:83], v[202:205], v[96:99], v[80:83]
	v_fmamk_f32 v88, v88, 0x3e0293ee, v250
	v_add_f32_e32 v196, v92, v196
	v_exp_f32_e32 v88, v88
	v_mfma_f32_16x16x32_bf16 v[76:79], v[206:209], v[96:99], v[76:79]
	v_fmamk_f32 v89, v89, 0x3e0293ee, v250
	v_add_f32_e32 v196, v93, v196
	v_exp_f32_e32 v89, v89
	v_mfma_f32_16x16x32_bf16 v[72:75], v[230:233], v[96:99], v[72:75]
	v_fmamk_f32 v90, v90, 0x3e0293ee, v250
	v_add_f32_e32 v196, v94, v196
	v_exp_f32_e32 v90, v90
	v_mfma_f32_16x16x32_bf16 v[68:71], v[234:237], v[96:99], v[68:71]
	v_fmamk_f32 v91, v91, 0x3e0293ee, v250
	v_add_f32_e32 v196, v95, v196
	v_exp_f32_e32 v91, v91
	ds_read_b128 v[202:205], v195 offset:35008
	ds_read_b128 v[206:209], v195 offset:35280
	ds_read_b128 v[230:233], v195 offset:43712
	ds_read_b128 v[234:237], v195 offset:43984
	s_waitcnt lgkmcnt(4)
	v_mfma_f32_16x16x32_bf16 v[64:67], v[238:241], v[96:99], v[64:67]
	v_add_f32_e32 v196, v88, v196
	v_add_f32_e32 v196, v89, v196
	v_add_f32_e32 v196, v90, v196
	v_fmamk_f32 v84, v84, 0x3e0293ee, v250
	v_mfma_f32_16x16x32_bf16 v[60:63], v[242:245], v[96:99], v[60:63]
	v_add_f32_e32 v223, v91, v196
	v_exp_f32_e32 v196, v84
	v_fmamk_f32 v85, v85, 0x3e0293ee, v250
	v_exp_f32_e32 v85, v85
	v_mfma_f32_16x16x32_bf16 v[56:59], v[246:249], v[96:99], v[56:59]
	v_fmamk_f32 v86, v86, 0x3e0293ee, v250
	v_exp_f32_e32 v86, v86
	v_fmac_f32_e32 v250, 0x3e0293ee, v87
	v_exp_f32_e32 v87, v250
	v_mfma_f32_16x16x32_bf16 v[52:55], v[198:201], v[96:99], v[52:55]
	v_add_f32_e32 v84, v196, v223
	v_add_f32_e32 v84, v85, v84
	v_add_f32_e32 v84, v86, v84
	v_add_f32_e32 v250, v87, v84
	v_cvt_pk_bf16_f32 v88, v88, v89
	v_cvt_pk_bf16_f32 v89, v90, v91
	v_cvt_pk_bf16_f32 v90, v196, v85
	v_cvt_pk_bf16_f32 v91, v86, v87
	ds_read_b128 v[238:241], v195 offset:52416
	ds_read_b128 v[242:245], v195 offset:52688
	ds_read_b128 v[246:249], v195 offset:61120
	ds_read_b128 v[198:201], v195 offset:61392
	s_waitcnt lgkmcnt(4)
	v_mfma_f32_16x16x32_bf16 v[80:83], v[202:205], v[88:91], v[80:83]
	v_mov_b32_e32 v251, v250
	s_nop 1
	v_permlane16_swap_b32_e32 v250, v251
	v_add_f32_e32 v250, v250, v251
	v_mfma_f32_16x16x32_bf16 v[76:79], v[206:209], v[88:91], v[76:79]
	v_mov_b32_e32 v251, v250
	s_nop 1
	v_permlane32_swap_b32_e32 v250, v251
	v_add_f32_e32 v250, v250, v251
	v_fmac_f32_e32 v250, v194, v224
	v_mfma_f32_16x16x32_bf16 v[72:75], v[230:233], v[88:91], v[72:75]
	v_mfma_f32_16x16x32_bf16 v[68:71], v[234:237], v[88:91], v[68:71]
	s_waitcnt lgkmcnt(0)
	v_mfma_f32_16x16x32_bf16 v[64:67], v[238:241], v[88:91], v[64:67]
	v_mfma_f32_16x16x32_bf16 v[60:63], v[242:245], v[88:91], v[60:63]
	v_mfma_f32_16x16x32_bf16 v[56:59], v[246:249], v[88:91], v[56:59]
	v_mfma_f32_16x16x32_bf16 v[52:55], v[198:201], v[88:91], v[52:55]
	v_mov_b32_e32 v194, v250
	s_andn2_b64 vcc, exec, s[8:9]
	s_xor_b32 s15, s15, 1
	s_cbranch_vccnz .LBB0_138
	s_branch .LBB0_92
